# P7 epilogue in four quarter batches with two quarters of x1 loads always in flight; plain output stores
# speedup vs baseline: 1.0156x; 1.0016x over previous
;     __device__ __forceinline__ void operator()(const pg8::f32x4 (&acc)[2][2][4][2], const pg8::Unit& u, int wr, int wc, int fr, int fq) const {
;         const int b = u.pm >> 4;
; #pragma unroll
;         for (int bj = 0; bj < 2; ++bj) { const int c0 = u.pn * 256 + bj * 128 + wc * 32 + 8 * fq; const float* g2p = e.mod + (size_t)b * NMOD + 5 * DM + c0; const f32x4 ga = *(const f32x4*)g2p, gb = *(const f32x4*)(g2p + 4);
; #pragma unroll
;             for (int ai = 0; ai < 2; ++ai)
; #pragma unroll
;                 for (int m = 0; m < 4; ++m) { ACC8(v, ai, bj, m); const size_t off = (size_t)(u.pm * 256 + ai * 128 + wr * 64 + m * 16 + fr) * DM + c0;
;                     f32x4 xa = __builtin_nontemporal_load((const f32x4*)(e.out + off)), xc = __builtin_nontemporal_load((const f32x4*)(e.out + off + 4));
; #pragma unroll
;                     for (int i = 0; i < 4; ++i) { xa[i] += ga[i] * v[i]; xc[i] += gb[i] * v[4 + i]; }
;                     float* dst = e.dump ? e.dump + (off & (size_t)0x7ffff8) : e.out + off;
;                     __builtin_nontemporal_store(xa, (f32x4*)dst); __builtin_nontemporal_store(xc, (f32x4*)(dst + 4)); }
.LBB9_856:
	s_ashr_i32 s14, s37, 4
	v_lshl_add_u32 v166, s37, 8, v170
	s_mul_hi_i32 s15, s14, 0x6000
	s_mulk_i32 s14, 0x6000
	v_ashrrev_i32_e32 v167, 31, v166
	s_add_u32 s14, s90, s14
	v_lshlrev_b64 v[152:153], 12, v[166:167]
	v_or_b32_e32 v154, 16, v166
	v_or_b32_e32 v156, 32, v166
	v_or_b32_e32 v158, 48, v166
	v_add_u32_e32 v160, 0x80, v166
	v_add_u32_e32 v162, 0x90, v166
	v_add_u32_e32 v164, 0xa0, v166
	v_add_u32_e32 v166, 0xb0, v166
	v_lshl_or_b32 v168, s38, 8, v172
	s_addc_u32 s15, s91, s15
	v_ashrrev_i32_e32 v155, 31, v154
	v_ashrrev_i32_e32 v157, 31, v156
	v_ashrrev_i32_e32 v159, 31, v158
	v_ashrrev_i32_e32 v161, 31, v160
	v_ashrrev_i32_e32 v163, 31, v162
	v_ashrrev_i32_e32 v165, 31, v164
	v_ashrrev_i32_e32 v167, 31, v166
	s_add_u32 s14, s14, 0x1f45000
	v_ashrrev_i32_e32 v169, 31, v168
	v_lshlrev_b64 v[154:155], 12, v[154:155]
	v_lshlrev_b64 v[156:157], 12, v[156:157]
	v_lshlrev_b64 v[158:159], 12, v[158:159]
	v_lshlrev_b64 v[160:161], 12, v[160:161]
	v_lshlrev_b64 v[162:163], 12, v[162:163]
	v_lshlrev_b64 v[164:165], 12, v[164:165]
	v_lshlrev_b64 v[166:167], 12, v[166:167]
	s_addc_u32 s15, s15, 0
	v_lshlrev_b64 v[232:233], 2, v[168:169]
	v_lshl_add_u64 v[152:153], s[88:89], 0, v[152:153]
	v_lshl_add_u64 v[154:155], s[88:89], 0, v[154:155]
	v_lshl_add_u64 v[156:157], s[88:89], 0, v[156:157]
	v_lshl_add_u64 v[158:159], s[88:89], 0, v[158:159]
	v_lshl_add_u64 v[160:161], s[88:89], 0, v[160:161]
	v_lshl_add_u64 v[162:163], s[88:89], 0, v[162:163]
	v_lshl_add_u64 v[164:165], s[88:89], 0, v[164:165]
	v_lshl_add_u64 v[166:167], s[88:89], 0, v[166:167]
	v_lshl_add_u64 v[132:133], s[14:15], 0, v[232:233]
	v_lshl_add_u64 v[152:153], v[152:153], 0, v[232:233]
	v_lshl_add_u64 v[154:155], v[154:155], 0, v[232:233]
	v_lshl_add_u64 v[156:157], v[156:157], 0, v[232:233]
	v_lshl_add_u64 v[158:159], v[158:159], 0, v[232:233]
	v_lshl_add_u64 v[160:161], v[160:161], 0, v[232:233]
	v_lshl_add_u64 v[162:163], v[162:163], 0, v[232:233]
	v_lshl_add_u64 v[164:165], v[164:165], 0, v[232:233]
	v_lshl_add_u64 v[166:167], v[166:167], 0, v[232:233]
	global_load_dwordx4 v[128:131], v[132:133], off offset:16
	s_nop 0
	global_load_dwordx4 v[132:135], v[132:133], off
	v_or_b32_e32 v248, 0x80, v168
	v_ashrrev_i32_e32 v249, 31, v248
	v_lshl_add_u64 v[248:249], v[248:249], 2, s[14:15]
	global_load_dwordx4 v[240:243], v[248:249], off
	global_load_dwordx4 v[244:247], v[248:249], off offset:16
	global_load_dwordx4 v[176:179], v[152:153], off nt
	global_load_dwordx4 v[180:183], v[152:153], off offset:16 nt
	global_load_dwordx4 v[184:187], v[154:155], off nt
	global_load_dwordx4 v[188:191], v[154:155], off offset:16 nt
	global_load_dwordx4 v[192:195], v[156:157], off nt
	global_load_dwordx4 v[196:199], v[156:157], off offset:16 nt
	global_load_dwordx4 v[200:203], v[158:159], off nt
	global_load_dwordx4 v[204:207], v[158:159], off offset:16 nt
	global_load_dwordx4 v[208:211], v[160:161], off nt
	global_load_dwordx4 v[212:215], v[160:161], off offset:16 nt
	global_load_dwordx4 v[216:219], v[162:163], off nt
	global_load_dwordx4 v[220:223], v[162:163], off offset:16 nt
	global_load_dwordx4 v[224:227], v[164:165], off nt
	global_load_dwordx4 v[228:231], v[164:165], off offset:16 nt
	global_load_dwordx4 v[232:235], v[166:167], off nt
	global_load_dwordx4 v[236:239], v[166:167], off offset:16 nt
	s_and_b64 vcc, exec, s[0:1]
	s_mov_b64 s[0:1], -1
	s_waitcnt vmcnt(8)
	v_pk_fma_f32 v[124:125], v[124:125], v[132:133], v[176:177]
	v_pk_fma_f32 v[126:127], v[126:127], v[134:135], v[178:179]
	v_pk_fma_f32 v[120:121], v[120:121], v[128:129], v[180:181]
	v_pk_fma_f32 v[122:123], v[122:123], v[130:131], v[182:183]
	v_pk_fma_f32 v[116:117], v[116:117], v[132:133], v[184:185]
	v_pk_fma_f32 v[118:119], v[118:119], v[134:135], v[186:187]
	v_pk_fma_f32 v[112:113], v[112:113], v[128:129], v[188:189]
	v_pk_fma_f32 v[114:115], v[114:115], v[130:131], v[190:191]
	v_pk_fma_f32 v[108:109], v[108:109], v[132:133], v[192:193]
	v_pk_fma_f32 v[110:111], v[110:111], v[134:135], v[194:195]
	v_pk_fma_f32 v[104:105], v[104:105], v[128:129], v[196:197]
	v_pk_fma_f32 v[106:107], v[106:107], v[130:131], v[198:199]
	v_pk_fma_f32 v[100:101], v[100:101], v[132:133], v[200:201]
	v_pk_fma_f32 v[102:103], v[102:103], v[134:135], v[202:203]
	v_pk_fma_f32 v[96:97], v[96:97], v[128:129], v[204:205]
	v_pk_fma_f32 v[98:99], v[98:99], v[130:131], v[206:207]
	global_load_dwordx4 v[176:179], v[152:153], off offset:512 nt
	global_load_dwordx4 v[180:183], v[152:153], off offset:528 nt
	global_load_dwordx4 v[184:187], v[154:155], off offset:512 nt
	global_load_dwordx4 v[188:191], v[154:155], off offset:528 nt
	global_load_dwordx4 v[192:195], v[156:157], off offset:512 nt
	global_load_dwordx4 v[196:199], v[156:157], off offset:528 nt
	global_load_dwordx4 v[200:203], v[158:159], off offset:512 nt
	global_load_dwordx4 v[204:207], v[158:159], off offset:528 nt
	global_store_dwordx4 v[152:153], v[124:127], off
	global_store_dwordx4 v[152:153], v[120:123], off offset:16
	global_store_dwordx4 v[154:155], v[116:119], off
	global_store_dwordx4 v[154:155], v[112:115], off offset:16
	global_store_dwordx4 v[156:157], v[108:111], off
	global_store_dwordx4 v[156:157], v[104:107], off offset:16
	global_store_dwordx4 v[158:159], v[100:103], off
	global_store_dwordx4 v[158:159], v[96:99], off offset:16
	s_waitcnt vmcnt(16)
;     __device__ __forceinline__ void operator()(const pg8::f32x4 (&acc)[2][2][4][2], const pg8::Unit& u, int wr, int wc, int fr, int fq) const {
;         const int b = u.pm >> 4;
; #pragma unroll
;         for (int bj = 0; bj < 2; ++bj) { const int c0 = u.pn * 256 + bj * 128 + wc * 32 + 8 * fq; const float* g2p = e.mod + (size_t)b * NMOD + 5 * DM + c0; const f32x4 ga = *(const f32x4*)g2p, gb = *(const f32x4*)(g2p + 4);
; #pragma unroll
;             for (int ai = 0; ai < 2; ++ai)
; #pragma unroll
;                 for (int m = 0; m < 4; ++m) { ACC8(v, ai, bj, m); const size_t off = (size_t)(u.pm * 256 + ai * 128 + wr * 64 + m * 16 + fr) * DM + c0;
;                     f32x4 xa = __builtin_nontemporal_load((const f32x4*)(e.out + off)), xc = __builtin_nontemporal_load((const f32x4*)(e.out + off + 4));
; #pragma unroll
;                     for (int i = 0; i < 4; ++i) { xa[i] += ga[i] * v[i]; xc[i] += gb[i] * v[4 + i]; }
;                     float* dst = e.dump ? e.dump + (off & (size_t)0x7ffff8) : e.out + off;
;                     __builtin_nontemporal_store(xa, (f32x4*)dst); __builtin_nontemporal_store(xc, (f32x4*)(dst + 4)); }
	v_pk_fma_f32 v[92:93], v[92:93], v[132:133], v[208:209]
	v_pk_fma_f32 v[94:95], v[94:95], v[134:135], v[210:211]
	v_pk_fma_f32 v[88:89], v[88:89], v[128:129], v[212:213]
	v_pk_fma_f32 v[90:91], v[90:91], v[130:131], v[214:215]
	v_pk_fma_f32 v[84:85], v[84:85], v[132:133], v[216:217]
	v_pk_fma_f32 v[86:87], v[86:87], v[134:135], v[218:219]
	v_pk_fma_f32 v[80:81], v[80:81], v[128:129], v[220:221]
	v_pk_fma_f32 v[82:83], v[82:83], v[130:131], v[222:223]
	v_pk_fma_f32 v[76:77], v[76:77], v[132:133], v[224:225]
	v_pk_fma_f32 v[78:79], v[78:79], v[134:135], v[226:227]
	v_pk_fma_f32 v[72:73], v[72:73], v[128:129], v[228:229]
	v_pk_fma_f32 v[74:75], v[74:75], v[130:131], v[230:231]
	v_pk_fma_f32 v[68:69], v[68:69], v[132:133], v[232:233]
	v_pk_fma_f32 v[70:71], v[70:71], v[134:135], v[234:235]
	v_pk_fma_f32 v[64:65], v[64:65], v[128:129], v[236:237]
	v_pk_fma_f32 v[66:67], v[66:67], v[130:131], v[238:239]
	global_load_dwordx4 v[208:211], v[160:161], off offset:512 nt
	global_load_dwordx4 v[212:215], v[160:161], off offset:528 nt
	global_load_dwordx4 v[216:219], v[162:163], off offset:512 nt
	global_load_dwordx4 v[220:223], v[162:163], off offset:528 nt
	global_load_dwordx4 v[224:227], v[164:165], off offset:512 nt
	global_load_dwordx4 v[228:231], v[164:165], off offset:528 nt
	global_load_dwordx4 v[232:235], v[166:167], off offset:512 nt
	global_load_dwordx4 v[236:239], v[166:167], off offset:528 nt
	global_store_dwordx4 v[160:161], v[92:95], off
	global_store_dwordx4 v[160:161], v[88:91], off offset:16
	global_store_dwordx4 v[162:163], v[84:87], off
	global_store_dwordx4 v[162:163], v[80:83], off offset:16
	global_store_dwordx4 v[164:165], v[76:79], off
	global_store_dwordx4 v[164:165], v[72:75], off offset:16
	global_store_dwordx4 v[166:167], v[68:71], off
	global_store_dwordx4 v[166:167], v[64:67], off offset:16
	s_waitcnt vmcnt(24)
	v_pk_fma_f32 v[60:61], v[60:61], v[240:241], v[176:177]
	v_pk_fma_f32 v[62:63], v[62:63], v[242:243], v[178:179]
	v_pk_fma_f32 v[56:57], v[56:57], v[244:245], v[180:181]
	v_pk_fma_f32 v[58:59], v[58:59], v[246:247], v[182:183]
	v_pk_fma_f32 v[52:53], v[52:53], v[240:241], v[184:185]
	v_pk_fma_f32 v[54:55], v[54:55], v[242:243], v[186:187]
	v_pk_fma_f32 v[48:49], v[48:49], v[244:245], v[188:189]
	v_pk_fma_f32 v[50:51], v[50:51], v[246:247], v[190:191]
	v_pk_fma_f32 v[44:45], v[44:45], v[240:241], v[192:193]
	v_pk_fma_f32 v[46:47], v[46:47], v[242:243], v[194:195]
	v_pk_fma_f32 v[40:41], v[40:41], v[244:245], v[196:197]
	v_pk_fma_f32 v[42:43], v[42:43], v[246:247], v[198:199]
	v_pk_fma_f32 v[36:37], v[36:37], v[240:241], v[200:201]
	v_pk_fma_f32 v[38:39], v[38:39], v[242:243], v[202:203]
	v_pk_fma_f32 v[32:33], v[32:33], v[244:245], v[204:205]
	v_pk_fma_f32 v[34:35], v[34:35], v[246:247], v[206:207]
	global_store_dwordx4 v[152:153], v[60:63], off offset:512
	global_store_dwordx4 v[152:153], v[56:59], off offset:528
	global_store_dwordx4 v[154:155], v[52:55], off offset:512
	global_store_dwordx4 v[154:155], v[48:51], off offset:528
	global_store_dwordx4 v[156:157], v[44:47], off offset:512
	global_store_dwordx4 v[156:157], v[40:43], off offset:528
	global_store_dwordx4 v[158:159], v[36:39], off offset:512
	global_store_dwordx4 v[158:159], v[32:35], off offset:528
	s_waitcnt vmcnt(16)
	v_pk_fma_f32 v[28:29], v[28:29], v[240:241], v[208:209]
	v_pk_fma_f32 v[30:31], v[30:31], v[242:243], v[210:211]
	v_pk_fma_f32 v[24:25], v[24:25], v[244:245], v[212:213]
	v_pk_fma_f32 v[26:27], v[26:27], v[246:247], v[214:215]
	v_pk_fma_f32 v[20:21], v[20:21], v[240:241], v[216:217]
	v_pk_fma_f32 v[22:23], v[22:23], v[242:243], v[218:219]
	v_pk_fma_f32 v[16:17], v[16:17], v[244:245], v[220:221]
	v_pk_fma_f32 v[18:19], v[18:19], v[246:247], v[222:223]
	v_pk_fma_f32 v[12:13], v[12:13], v[240:241], v[224:225]
	v_pk_fma_f32 v[14:15], v[14:15], v[242:243], v[226:227]
	v_pk_fma_f32 v[8:9], v[8:9], v[244:245], v[228:229]
	v_pk_fma_f32 v[10:11], v[10:11], v[246:247], v[230:231]
	v_pk_fma_f32 v[4:5], v[4:5], v[240:241], v[232:233]
	v_pk_fma_f32 v[6:7], v[6:7], v[242:243], v[234:235]
	v_pk_fma_f32 v[0:1], v[0:1], v[244:245], v[236:237]
	v_pk_fma_f32 v[2:3], v[2:3], v[246:247], v[238:239]
	global_store_dwordx4 v[160:161], v[28:31], off offset:512
	global_store_dwordx4 v[160:161], v[24:27], off offset:528
	global_store_dwordx4 v[162:163], v[20:23], off offset:512
	global_store_dwordx4 v[162:163], v[16:19], off offset:528
	global_store_dwordx4 v[164:165], v[12:15], off offset:512
	global_store_dwordx4 v[164:165], v[8:11], off offset:528
	global_store_dwordx4 v[166:167], v[4:7], off offset:512
	global_store_dwordx4 v[166:167], v[0:3], off offset:528
	s_cbranch_vccnz .LBB9_841
	s_andn2_b64 vcc, exec, s[6:7]
	s_cbranch_vccnz .LBB9_840
	s_barrier
	s_branch .LBB9_840
